# v100 + static s_setprio 1 for waves 4-7 inside the MLA fast path (reset at its exit)
# speedup vs baseline: 1.0103x; 1.0103x over previous
.Lmla_fast:
	s_mov_b32 s42, s30
	s_cmp_lt_u32 s5, 0x1000
	s_cbranch_scc1 .Lmla_fast_prio
	s_setprio 1

.Lmla_fast_generic:
	s_setprio 0
	s_sub_i32 s42, s30, s42
	s_lshl_b32 s42, s42, 6
	v_subrev_u32_e32 v146, s42, v146
	s_cmp_lg_u32 s20, s30
	s_cbranch_scc1 .LBB0_478
	s_branch .LBB0_430
